# grid barrier after phase 13 made control-only: no L2 writeback by the leaders and no L1 invalidate (the gates GEMM reads only phase-1 data; phase-13 writes are flushed at the next barrier)
# baseline (speedup 1.0000x reference)
.LBB0_784:
	s_or_b64 exec, exec, s[26:27]
	s_waitcnt vmcnt(0)
	v_readlane_b32 s16, v254, 38
	s_nop 3
	s_cmp_eq_u32 s16, 14
	s_cbranch_scc1 .Lb13_a
	buffer_inv sc1

.LBB0_785:
	s_andn2_saveexec_b64 s[16:17], s[22:23]
	s_cbranch_execz .LBB0_805
	s_mov_b64 s[22:23], exec
	v_readlane_b32 s16, v254, 38
	s_nop 3
	s_cmp_eq_u32 s16, 14
	s_cbranch_scc1 .Lb13_b
	buffer_wbl2 sc1
.Lb13_b:
	s_waitcnt lgkmcnt(0)
	s_waitcnt vmcnt(0)
	v_mbcnt_lo_u32_b32 v0, s22, 0
	v_mbcnt_hi_u32_b32 v0, s23, v0
	v_cmp_eq_u32_e32 vcc, 0, v0
	s_and_saveexec_b64 s[26:27], vcc
	s_cbranch_execz .LBB0_788
	s_bcnt1_i32_b64 s2, s[22:23]
	v_readlane_b32 s16, v251, 11
	v_mov_b32_e32 v3, s2
	v_readlane_b32 s17, v251, 12
	s_nop 4
	global_atomic_add v3, v1, v3, s[16:17] sc0

.Lsb_wait_l2:
	s_mov_b64 s[22:23], exec
	v_mbcnt_lo_u32_b32 v0, s22, 0
	v_mbcnt_hi_u32_b32 v0, s23, v0
	v_cmp_eq_u32_e32 vcc, 0, v0
	s_waitcnt vmcnt(0)
	v_readlane_b32 s16, v254, 38
	s_nop 3
	s_cmp_eq_u32 s16, 14
	s_cbranch_scc1 .Lb13_c
	buffer_inv sc1
.Lb13_c:
	s_and_saveexec_b64 s[26:27], vcc
	s_cbranch_execz .LBB0_804
	s_bcnt1_i32_b64 s2, s[22:23]
	v_readlane_b32 s16, v251, 9
	v_mov_b32_e32 v0, s2
	v_readlane_b32 s17, v251, 10
	s_nop 4
	global_atomic_add v1, v0, s[16:17]
